# barrier/queue poll loops: s_sleep 1 back-off replaced by s_nop (tighter wake-up), on top of v31
# speedup vs baseline: 1.0027x; 1.0027x over previous
; __global__ void __launch_bounds__(NT) fwd_megakernel(Params P0) {
;     ...
;   grid.sync();
.LBB0_99:
	s_nop 0
	global_load_dword v2, v0, s[2:3] offset:32 sc1
	s_waitcnt vmcnt(0)
	v_and_b32_e32 v2, 0xffff0000, v2
	v_cmp_ne_u32_e32 vcc, v2, v1
	s_or_b64 s[4:5], vcc, s[4:5]
	s_andn2_b64 exec, exec, s[4:5]
	s_cbranch_execnz .LBB0_99

; DI unsigned xb_ld(unsigned* p)              { return __hip_atomic_load(p, __ATOMIC_RELAXED, __HIP_MEMORY_SCOPE_AGENT); }
; DI void xcd_barrier_complete(unsigned* bar, unsigned x, unsigned& nloc, unsigned& nx) {
;     ...
;   for (;;) {
;     sum = 0u; cnt = 0u; mine = 0u;
; #pragma unroll
;     for (unsigned j = 0; j < 16; ++j) { const unsigned c = xb_ld(&bar[XB_XCNT(j)]); sum += c; cnt += (c > 0u) ? 1u : 0u; mine = (j == x) ? c : mine; }
;     if (sum == G) break;
;     __builtin_amdgcn_s_sleep(1);
;     if ((++sp & 255u) == 0u) { if (xb_ld(&bar[XB_TMO])) break; if (sp > XB_SPIN_CAP) { atomicAdd(&bar[XB_TMO], 1u); break; } }
;   }
.LBB0_116:
	global_load_dword v15, v16, s[4:5] sc1
	s_waitcnt lgkmcnt(0)
	global_load_dword v0, v16, s[6:7] sc1
	global_load_dword v1, v16, s[8:9] sc1
	global_load_dword v2, v16, s[10:11] sc1
	global_load_dword v3, v16, s[12:13] sc1
	global_load_dword v4, v16, s[14:15] sc1
	global_load_dword v5, v16, s[16:17] sc1
	global_load_dword v6, v16, s[18:19] sc1
	global_load_dword v7, v16, s[20:21] sc1
	global_load_dword v8, v16, s[22:23] sc1
	global_load_dword v9, v16, s[24:25] sc1
	global_load_dword v10, v16, s[26:27] sc1
	global_load_dword v11, v16, s[28:29] sc1
	global_load_dword v12, v16, s[30:31] sc1
	global_load_dword v13, v16, s[34:35] sc1
	global_load_dword v14, v16, s[36:37] sc1
	s_mov_b64 s[38:39], -1
	s_mov_b64 s[44:45], -1
	s_waitcnt vmcnt(14)
	v_add_u32_e32 v17, v0, v15
	s_waitcnt vmcnt(13)
	v_add_u32_e32 v17, v17, v1
	s_waitcnt vmcnt(12)
	v_add_u32_e32 v17, v17, v2
	s_waitcnt vmcnt(11)
	v_add_u32_e32 v17, v17, v3
	s_waitcnt vmcnt(10)
	v_add_u32_e32 v17, v17, v4
	s_waitcnt vmcnt(9)
	v_add_u32_e32 v17, v17, v5
	s_waitcnt vmcnt(8)
	v_add_u32_e32 v17, v17, v6
	s_waitcnt vmcnt(7)
	v_add_u32_e32 v17, v17, v7
	s_waitcnt vmcnt(6)
	v_add_u32_e32 v17, v17, v8
	s_waitcnt vmcnt(5)
	v_add_u32_e32 v17, v17, v9
	s_waitcnt vmcnt(4)
	v_add_u32_e32 v17, v17, v10
	s_waitcnt vmcnt(3)
	v_add_u32_e32 v17, v17, v11
	s_waitcnt vmcnt(2)
	v_add_u32_e32 v17, v17, v12
	s_waitcnt vmcnt(1)
	v_add_u32_e32 v17, v17, v13
	s_waitcnt vmcnt(0)
	v_add_u32_e32 v17, v17, v14
	v_cmp_eq_u32_e32 vcc, s49, v17
	s_cbranch_vccnz .LBB0_115
	s_and_b32 s38, s50, 0xff
	s_cmp_eq_u32 s38, 0
	s_mov_b64 s[38:39], -1
	s_mov_b64 s[46:47], -1
	s_nop 0
	s_cbranch_scc0 .LBB0_120
	global_load_dword v17, v16, s[2:3] sc1
	s_waitcnt vmcnt(0)
	v_cmp_eq_u32_e32 vcc, 0, v17
	s_cbranch_vccnz .LBB0_122
	s_mov_b64 s[46:47], 0

; DI unsigned xb_ld(unsigned* p)              { return __hip_atomic_load(p, __ATOMIC_RELAXED, __HIP_MEMORY_SCOPE_AGENT); }
; DI unsigned xb_add(unsigned* p, unsigned v) { return __hip_atomic_fetch_add(p, v, __ATOMIC_RELAXED, __HIP_MEMORY_SCOPE_AGENT); }
; #define XB_SPIN(cond, bar) do { unsigned _sp = 0; while (cond) { __builtin_amdgcn_s_sleep(1); \
;     if ((++_sp & 255u) == 0u) { if (xb_ld(&(bar)[XB_TMO])) break; if (_sp > XB_SPIN_CAP) { atomicAdd(&(bar)[XB_TMO], 1u); break; } } } } while (0)
; DI void xcd_barrier(char* ws_, char* smem_) {
;     ...
;       else XB_SPIN(xb_ld(&bar[XB_TOPGEN]) == tg, bar);
;       __builtin_amdgcn_fence(__ATOMIC_ACQUIRE, "agent");
;       xb_add(&bar[XB_XGEN(b.x)], 1u);
;       asm volatile("s_waitcnt vmcnt(0)" ::: "memory");
;     } else {
;       XB_SPIN(xb_ld(&bar[XB_XGEN(b.x)]) == gen, bar);
.LBB0_134:
	s_and_b32 s18, s22, 0xff
	s_mov_b64 s[16:17], -1
	s_cmp_lg_u32 s18, 0
	s_mov_b64 s[20:21], -1
	s_nop 0
	s_cbranch_scc1 .LBB0_137
	global_load_dword v2, v0, s[8:9] sc1
	s_waitcnt vmcnt(0)
	v_cmp_eq_u32_e32 vcc, 0, v2
	s_cbranch_vccnz .LBB0_139
	s_mov_b64 s[20:21], 0
	s_mov_b64 s[18:19], -1

; DI unsigned xb_ld(unsigned* p)              { return __hip_atomic_load(p, __ATOMIC_RELAXED, __HIP_MEMORY_SCOPE_AGENT); }
; DI unsigned xb_add(unsigned* p, unsigned v) { return __hip_atomic_fetch_add(p, v, __ATOMIC_RELAXED, __HIP_MEMORY_SCOPE_AGENT); }
; #define XB_SPIN(cond, bar) do { unsigned _sp = 0; while (cond) { __builtin_amdgcn_s_sleep(1); \
;     if ((++_sp & 255u) == 0u) { if (xb_ld(&(bar)[XB_TMO])) break; if (_sp > XB_SPIN_CAP) { atomicAdd(&(bar)[XB_TMO], 1u); break; } } } } while (0)
; DI void xcd_barrier(char* ws_, char* smem_) {
;     ...
;       else XB_SPIN(xb_ld(&bar[XB_TOPGEN]) == tg, bar);
;       __builtin_amdgcn_fence(__ATOMIC_ACQUIRE, "agent");
;       xb_add(&bar[XB_XGEN(b.x)], 1u);
;       asm volatile("s_waitcnt vmcnt(0)" ::: "memory");
;     } else {
;       XB_SPIN(xb_ld(&bar[XB_XGEN(b.x)]) == gen, bar);
.LBB0_151:
	s_and_b32 s16, s22, 0xff
	s_cmp_lg_u32 s16, 0
	s_mov_b64 s[18:19], -1
	s_nop 0
	s_cbranch_scc1 .LBB0_154
	global_load_dword v1, v0, s[8:9] sc1
	s_waitcnt vmcnt(0)
	v_cmp_eq_u32_e32 vcc, 0, v1
	s_cbranch_vccnz .LBB0_156
	s_mov_b64 s[18:19], 0
	s_mov_b64 s[16:17], -1

; DI unsigned xb_ld(unsigned* p)              { return __hip_atomic_load(p, __ATOMIC_RELAXED, __HIP_MEMORY_SCOPE_AGENT); }
; DI void xcd_barrier_complete(unsigned* bar, unsigned x, unsigned& nloc, unsigned& nx) {
;   const unsigned G = gridDim.x * gridDim.y * gridDim.z;
;   unsigned sum, cnt, mine, sp = 0u;
;   for (;;) {
;     sum = 0u; cnt = 0u; mine = 0u;
; #pragma unroll
;     for (unsigned j = 0; j < 16; ++j) { const unsigned c = xb_ld(&bar[XB_XCNT(j)]); sum += c; cnt += (c > 0u) ? 1u : 0u; mine = (j == x) ? c : mine; }
;     if (sum == G) break;
;     __builtin_amdgcn_s_sleep(1);
;     if ((++sp & 255u) == 0u) { if (xb_ld(&bar[XB_TMO])) break; if (sp > XB_SPIN_CAP) { atomicAdd(&bar[XB_TMO], 1u); break; } }
;   }
.LBB0_226:
	v_readlane_b32 s0, v254, 29
	v_readlane_b32 s1, v254, 30
	s_mov_b64 s[4:5], -1
	s_mov_b64 s[8:9], -1
	s_nop 2
	global_load_dword v0, v1, s[0:1] sc1
	v_readlane_b32 s0, v254, 31
	v_readlane_b32 s1, v254, 32
	s_waitcnt lgkmcnt(0)
	s_nop 3
	global_load_dword v2, v1, s[0:1] sc1
	v_readlane_b32 s0, v254, 33
	v_readlane_b32 s1, v254, 34
	s_waitcnt vmcnt(0)
	v_add_u32_e32 v17, v2, v0
	s_nop 2
	global_load_dword v3, v1, s[0:1] sc1
	v_readlane_b32 s0, v254, 35
	v_readlane_b32 s1, v254, 36
	s_waitcnt vmcnt(0)
	v_add_u32_e32 v17, v17, v3
	s_nop 2
	global_load_dword v4, v1, s[0:1] sc1
	v_readlane_b32 s0, v254, 37
	v_readlane_b32 s1, v254, 38
	s_waitcnt vmcnt(0)
	v_add_u32_e32 v17, v17, v4
	s_nop 2
	global_load_dword v5, v1, s[0:1] sc1
	v_readlane_b32 s0, v254, 39
	v_readlane_b32 s1, v254, 40
	s_waitcnt vmcnt(0)
	v_add_u32_e32 v17, v17, v5
	s_nop 2
	global_load_dword v6, v1, s[0:1] sc1
	v_readlane_b32 s0, v254, 41
	v_readlane_b32 s1, v254, 42
	s_waitcnt vmcnt(0)
	v_add_u32_e32 v17, v17, v6
	s_nop 2
	global_load_dword v7, v1, s[0:1] sc1
	v_readlane_b32 s0, v254, 43
	v_readlane_b32 s1, v254, 44
	s_waitcnt vmcnt(0)
	v_add_u32_e32 v17, v17, v7
	s_nop 2
	global_load_dword v8, v1, s[0:1] sc1
	v_readlane_b32 s0, v254, 45
	v_readlane_b32 s1, v254, 46
	s_waitcnt vmcnt(0)
	v_add_u32_e32 v17, v17, v8
	s_nop 2
	global_load_dword v9, v1, s[0:1] sc1
	v_readlane_b32 s0, v254, 47
	v_readlane_b32 s1, v254, 48
	s_waitcnt vmcnt(0)
	v_add_u32_e32 v17, v17, v9
	s_nop 2
	global_load_dword v10, v1, s[0:1] sc1
	v_readlane_b32 s0, v254, 49
	v_readlane_b32 s1, v254, 50
	s_waitcnt vmcnt(0)
	v_add_u32_e32 v17, v17, v10
	s_nop 2
	global_load_dword v11, v1, s[0:1] sc1
	v_readlane_b32 s0, v254, 51
	v_readlane_b32 s1, v254, 52
	s_nop 4
	global_load_dword v12, v1, s[0:1] sc1
	global_load_dword v13, v1, s[68:69] sc1
	global_load_dword v14, v1, s[74:75] sc1
	global_load_dword v15, v1, s[64:65] sc1
	global_load_dword v16, v1, s[72:73] sc1
	s_waitcnt vmcnt(5)
	v_add_u32_e32 v17, v17, v11
	s_waitcnt vmcnt(4)
	v_add_u32_e32 v17, v17, v12
	s_waitcnt vmcnt(3)
	v_add_u32_e32 v17, v17, v13
	s_waitcnt vmcnt(2)
	v_add_u32_e32 v17, v17, v14
	s_waitcnt vmcnt(1)
	v_add_u32_e32 v17, v17, v15
	s_waitcnt vmcnt(0)
	v_add_u32_e32 v17, v17, v16
	v_cmp_eq_u32_e32 vcc, s56, v17
	s_cbranch_vccnz .LBB0_225
	s_and_b32 s0, s13, 0xff
	s_cmp_eq_u32 s0, 0
	s_mov_b64 s[10:11], -1
	s_nop 0
	s_cbranch_scc0 .LBB0_230
	v_readlane_b32 s0, v254, 27
	v_readlane_b32 s1, v254, 28
	s_nop 4
	global_load_dword v17, v1, s[0:1] sc1
	s_waitcnt vmcnt(0)
	v_cmp_eq_u32_e32 vcc, 0, v17
	s_cbranch_vccnz .LBB0_232
	s_mov_b64 s[10:11], 0

; DI unsigned xb_ld(unsigned* p)              { return __hip_atomic_load(p, __ATOMIC_RELAXED, __HIP_MEMORY_SCOPE_AGENT); }
; DI unsigned xb_add(unsigned* p, unsigned v) { return __hip_atomic_fetch_add(p, v, __ATOMIC_RELAXED, __HIP_MEMORY_SCOPE_AGENT); }
; #define XB_SPIN(cond, bar) do { unsigned _sp = 0; while (cond) { __builtin_amdgcn_s_sleep(1); \
;     if ((++_sp & 255u) == 0u) { if (xb_ld(&(bar)[XB_TMO])) break; if (_sp > XB_SPIN_CAP) { atomicAdd(&(bar)[XB_TMO], 1u); break; } } } } while (0)
; DI void xcd_barrier(char* ws_, char* smem_) {
;     ...
;       else XB_SPIN(xb_ld(&bar[XB_TOPGEN]) == tg, bar);
;       __builtin_amdgcn_fence(__ATOMIC_ACQUIRE, "agent");
;       xb_add(&bar[XB_XGEN(b.x)], 1u);
;       asm volatile("s_waitcnt vmcnt(0)" ::: "memory");
;     } else {
;       XB_SPIN(xb_ld(&bar[XB_XGEN(b.x)]) == gen, bar);
.LBB0_244:
	s_and_b32 s0, s24, 0xff
	s_mov_b64 s[18:19], -1
	s_cmp_lg_u32 s0, 0
	s_mov_b64 s[22:23], -1
	s_nop 0
	s_cbranch_scc1 .LBB0_247
	v_readlane_b32 s0, v254, 27
	v_readlane_b32 s1, v254, 28
	s_nop 4
	global_load_dword v2, v1, s[0:1] sc1
	s_waitcnt vmcnt(0)
	v_cmp_eq_u32_e32 vcc, 0, v2
	s_cbranch_vccnz .LBB0_249
	s_mov_b64 s[22:23], 0
	s_mov_b64 s[20:21], -1

; DI unsigned xb_ld(unsigned* p)              { return __hip_atomic_load(p, __ATOMIC_RELAXED, __HIP_MEMORY_SCOPE_AGENT); }
; DI unsigned xb_add(unsigned* p, unsigned v) { return __hip_atomic_fetch_add(p, v, __ATOMIC_RELAXED, __HIP_MEMORY_SCOPE_AGENT); }
; #define XB_SPIN(cond, bar) do { unsigned _sp = 0; while (cond) { __builtin_amdgcn_s_sleep(1); \
;     if ((++_sp & 255u) == 0u) { if (xb_ld(&(bar)[XB_TMO])) break; if (_sp > XB_SPIN_CAP) { atomicAdd(&(bar)[XB_TMO], 1u); break; } } } } while (0)
; DI void xcd_barrier(char* ws_, char* smem_) {
;     ...
;       else XB_SPIN(xb_ld(&bar[XB_TOPGEN]) == tg, bar);
;       __builtin_amdgcn_fence(__ATOMIC_ACQUIRE, "agent");
;       xb_add(&bar[XB_XGEN(b.x)], 1u);
;       asm volatile("s_waitcnt vmcnt(0)" ::: "memory");
;     } else {
;       XB_SPIN(xb_ld(&bar[XB_XGEN(b.x)]) == gen, bar);
.LBB0_261:
	s_and_b32 s0, s22, 0xff
	s_mov_b64 s[16:17], -1
	s_cmp_lg_u32 s0, 0
	s_mov_b64 s[20:21], -1
	s_nop 0
	s_cbranch_scc1 .LBB0_264
	v_readlane_b32 s0, v254, 27
	v_readlane_b32 s1, v254, 28
	s_nop 4
	global_load_dword v2, v1, s[0:1] sc1
	s_waitcnt vmcnt(0)
	v_cmp_eq_u32_e32 vcc, 0, v2
	s_cbranch_vccnz .LBB0_266
	s_mov_b64 s[20:21], 0
	s_mov_b64 s[18:19], -1

; DI unsigned xb_ld(unsigned* p)              { return __hip_atomic_load(p, __ATOMIC_RELAXED, __HIP_MEMORY_SCOPE_AGENT); }
; DI void xcd_barrier_complete(unsigned* bar, unsigned x, unsigned& nloc, unsigned& nx) {
;   const unsigned G = gridDim.x * gridDim.y * gridDim.z;
;   unsigned sum, cnt, mine, sp = 0u;
;   for (;;) {
;     sum = 0u; cnt = 0u; mine = 0u;
; #pragma unroll
;     for (unsigned j = 0; j < 16; ++j) { const unsigned c = xb_ld(&bar[XB_XCNT(j)]); sum += c; cnt += (c > 0u) ? 1u : 0u; mine = (j == x) ? c : mine; }
;     if (sum == G) break;
;     __builtin_amdgcn_s_sleep(1);
;     if ((++sp & 255u) == 0u) { if (xb_ld(&bar[XB_TMO])) break; if (sp > XB_SPIN_CAP) { atomicAdd(&bar[XB_TMO], 1u); break; } }
;   }
.LBB0_536:
	v_readlane_b32 s2, v254, 29
	v_readlane_b32 s3, v254, 30
	s_mov_b64 s[4:5], -1
	s_nop 3
	global_load_dword v0, v1, s[2:3] sc1
	v_readlane_b32 s2, v254, 31
	v_readlane_b32 s3, v254, 32
	s_waitcnt lgkmcnt(0)
	s_nop 3
	global_load_dword v2, v1, s[2:3] sc1
	v_readlane_b32 s2, v254, 33
	v_readlane_b32 s3, v254, 34
	s_waitcnt vmcnt(0)
	v_add_u32_e32 v17, v2, v0
	s_nop 2
	global_load_dword v3, v1, s[2:3] sc1
	v_readlane_b32 s2, v254, 35
	v_readlane_b32 s3, v254, 36
	s_waitcnt vmcnt(0)
	v_add_u32_e32 v17, v17, v3
	s_nop 2
	global_load_dword v4, v1, s[2:3] sc1
	v_readlane_b32 s2, v254, 37
	v_readlane_b32 s3, v254, 38
	s_waitcnt vmcnt(0)
	v_add_u32_e32 v17, v17, v4
	s_nop 2
	global_load_dword v5, v1, s[2:3] sc1
	v_readlane_b32 s2, v254, 39
	v_readlane_b32 s3, v254, 40
	s_waitcnt vmcnt(0)
	v_add_u32_e32 v17, v17, v5
	s_nop 2
	global_load_dword v6, v1, s[2:3] sc1
	v_readlane_b32 s2, v254, 41
	v_readlane_b32 s3, v254, 42
	s_waitcnt vmcnt(0)
	v_add_u32_e32 v17, v17, v6
	s_nop 2
	global_load_dword v7, v1, s[2:3] sc1
	v_readlane_b32 s2, v254, 43
	v_readlane_b32 s3, v254, 44
	s_waitcnt vmcnt(0)
	v_add_u32_e32 v17, v17, v7
	s_nop 2
	global_load_dword v8, v1, s[2:3] sc1
	v_readlane_b32 s2, v254, 45
	v_readlane_b32 s3, v254, 46
	s_waitcnt vmcnt(0)
	v_add_u32_e32 v17, v17, v8
	s_nop 2
	global_load_dword v9, v1, s[2:3] sc1
	v_readlane_b32 s2, v254, 47
	v_readlane_b32 s3, v254, 48
	s_waitcnt vmcnt(0)
	v_add_u32_e32 v17, v17, v9
	s_nop 2
	global_load_dword v10, v1, s[2:3] sc1
	v_readlane_b32 s2, v254, 49
	v_readlane_b32 s3, v254, 50
	s_waitcnt vmcnt(0)
	v_add_u32_e32 v17, v17, v10
	s_nop 2
	global_load_dword v11, v1, s[2:3] sc1
	v_readlane_b32 s2, v254, 51
	v_readlane_b32 s3, v254, 52
	s_nop 4
	global_load_dword v12, v1, s[2:3] sc1
	global_load_dword v13, v1, s[68:69] sc1
	global_load_dword v14, v1, s[74:75] sc1
	global_load_dword v15, v1, s[64:65] sc1
	global_load_dword v16, v1, s[72:73] sc1
	s_mov_b64 s[2:3], -1
	s_waitcnt vmcnt(5)
	v_add_u32_e32 v17, v17, v11
	s_waitcnt vmcnt(4)
	v_add_u32_e32 v17, v17, v12
	s_waitcnt vmcnt(3)
	v_add_u32_e32 v17, v17, v13
	s_waitcnt vmcnt(2)
	v_add_u32_e32 v17, v17, v14
	s_waitcnt vmcnt(1)
	v_add_u32_e32 v17, v17, v15
	s_waitcnt vmcnt(0)
	v_add_u32_e32 v17, v17, v16
	v_cmp_eq_u32_e32 vcc, s56, v17
	s_cbranch_vccnz .LBB0_535
	s_and_b32 s2, s11, 0xff
	s_cmp_eq_u32 s2, 0
	s_mov_b64 s[2:3], -1
	s_mov_b64 s[8:9], -1
	s_nop 0
	s_cbranch_scc0 .LBB0_540
	v_readlane_b32 s2, v254, 27
	v_readlane_b32 s3, v254, 28
	s_nop 4
	global_load_dword v17, v1, s[2:3] sc1
	s_waitcnt vmcnt(0)
	v_cmp_eq_u32_e32 vcc, 0, v17
	s_cbranch_vccnz .LBB0_542
	s_mov_b64 s[8:9], 0
	s_mov_b64 s[2:3], -1

; DI unsigned xb_ld(unsigned* p)              { return __hip_atomic_load(p, __ATOMIC_RELAXED, __HIP_MEMORY_SCOPE_AGENT); }
; DI unsigned xb_add(unsigned* p, unsigned v) { return __hip_atomic_fetch_add(p, v, __ATOMIC_RELAXED, __HIP_MEMORY_SCOPE_AGENT); }
; #define XB_SPIN(cond, bar) do { unsigned _sp = 0; while (cond) { __builtin_amdgcn_s_sleep(1); \
;     if ((++_sp & 255u) == 0u) { if (xb_ld(&(bar)[XB_TMO])) break; if (_sp > XB_SPIN_CAP) { atomicAdd(&(bar)[XB_TMO], 1u); break; } } } } while (0)
; DI void xcd_barrier(char* ws_, char* smem_) {
;     ...
;       else XB_SPIN(xb_ld(&bar[XB_TOPGEN]) == tg, bar);
;       __builtin_amdgcn_fence(__ATOMIC_ACQUIRE, "agent");
;       xb_add(&bar[XB_XGEN(b.x)], 1u);
;       asm volatile("s_waitcnt vmcnt(0)" ::: "memory");
;     } else {
;       XB_SPIN(xb_ld(&bar[XB_XGEN(b.x)]) == gen, bar);
.LBB0_554:
	s_and_b32 s18, s22, 0xff
	s_mov_b64 s[16:17], -1
	s_cmp_lg_u32 s18, 0
	s_mov_b64 s[20:21], -1
	s_nop 0
	s_cbranch_scc1 .LBB0_557
	v_readlane_b32 s18, v254, 27
	v_readlane_b32 s19, v254, 28
	s_nop 4
	global_load_dword v2, v1, s[18:19] sc1
	s_waitcnt vmcnt(0)
	v_cmp_eq_u32_e32 vcc, 0, v2
	s_cbranch_vccnz .LBB0_559
	s_mov_b64 s[20:21], 0
	s_mov_b64 s[18:19], -1

; DI unsigned xb_ld(unsigned* p)              { return __hip_atomic_load(p, __ATOMIC_RELAXED, __HIP_MEMORY_SCOPE_AGENT); }
; DI unsigned xb_add(unsigned* p, unsigned v) { return __hip_atomic_fetch_add(p, v, __ATOMIC_RELAXED, __HIP_MEMORY_SCOPE_AGENT); }
; #define XB_SPIN(cond, bar) do { unsigned _sp = 0; while (cond) { __builtin_amdgcn_s_sleep(1); \
;     if ((++_sp & 255u) == 0u) { if (xb_ld(&(bar)[XB_TMO])) break; if (_sp > XB_SPIN_CAP) { atomicAdd(&(bar)[XB_TMO], 1u); break; } } } } while (0)
; DI void xcd_barrier(char* ws_, char* smem_) {
;     ...
;       else XB_SPIN(xb_ld(&bar[XB_TOPGEN]) == tg, bar);
;       __builtin_amdgcn_fence(__ATOMIC_ACQUIRE, "agent");
;       xb_add(&bar[XB_XGEN(b.x)], 1u);
;       asm volatile("s_waitcnt vmcnt(0)" ::: "memory");
;     } else {
;       XB_SPIN(xb_ld(&bar[XB_XGEN(b.x)]) == gen, bar);
.LBB0_571:
	s_and_b32 s16, s20, 0xff
	s_mov_b64 s[14:15], -1
	s_cmp_lg_u32 s16, 0
	s_mov_b64 s[18:19], -1
	s_nop 0
	s_cbranch_scc1 .LBB0_574
	v_readlane_b32 s16, v254, 27
	v_readlane_b32 s17, v254, 28
	s_nop 4
	global_load_dword v2, v1, s[16:17] sc1
	s_waitcnt vmcnt(0)
	v_cmp_eq_u32_e32 vcc, 0, v2
	s_cbranch_vccnz .LBB0_576
	s_mov_b64 s[18:19], 0
	s_mov_b64 s[16:17], -1

; DI unsigned xb_ld(unsigned* p)              { return __hip_atomic_load(p, __ATOMIC_RELAXED, __HIP_MEMORY_SCOPE_AGENT); }
; DI void xcd_barrier_complete(unsigned* bar, unsigned x, unsigned& nloc, unsigned& nx) {
;   const unsigned G = gridDim.x * gridDim.y * gridDim.z;
;   unsigned sum, cnt, mine, sp = 0u;
;   for (;;) {
;     sum = 0u; cnt = 0u; mine = 0u;
; #pragma unroll
;     for (unsigned j = 0; j < 16; ++j) { const unsigned c = xb_ld(&bar[XB_XCNT(j)]); sum += c; cnt += (c > 0u) ? 1u : 0u; mine = (j == x) ? c : mine; }
;     if (sum == G) break;
;     __builtin_amdgcn_s_sleep(1);
;     if ((++sp & 255u) == 0u) { if (xb_ld(&bar[XB_TMO])) break; if (sp > XB_SPIN_CAP) { atomicAdd(&bar[XB_TMO], 1u); break; } }
;   }
.LBB0_836:
	v_readlane_b32 s8, v254, 29
	v_readlane_b32 s9, v254, 30
	s_mov_b64 s[10:11], -1
	s_nop 3
	global_load_dword v0, v1, s[8:9] sc1
	v_readlane_b32 s8, v254, 31
	v_readlane_b32 s9, v254, 32
	s_waitcnt lgkmcnt(0)
	s_nop 3
	global_load_dword v2, v1, s[8:9] sc1
	v_readlane_b32 s8, v254, 33
	v_readlane_b32 s9, v254, 34
	s_waitcnt vmcnt(0)
	v_add_u32_e32 v17, v2, v0
	s_nop 2
	global_load_dword v3, v1, s[8:9] sc1
	v_readlane_b32 s8, v254, 35
	v_readlane_b32 s9, v254, 36
	s_waitcnt vmcnt(0)
	v_add_u32_e32 v17, v17, v3
	s_nop 2
	global_load_dword v4, v1, s[8:9] sc1
	v_readlane_b32 s8, v254, 37
	v_readlane_b32 s9, v254, 38
	s_waitcnt vmcnt(0)
	v_add_u32_e32 v17, v17, v4
	s_nop 2
	global_load_dword v5, v1, s[8:9] sc1
	v_readlane_b32 s8, v254, 39
	v_readlane_b32 s9, v254, 40
	s_waitcnt vmcnt(0)
	v_add_u32_e32 v17, v17, v5
	s_nop 2
	global_load_dword v6, v1, s[8:9] sc1
	v_readlane_b32 s8, v254, 41
	v_readlane_b32 s9, v254, 42
	s_waitcnt vmcnt(0)
	v_add_u32_e32 v17, v17, v6
	s_nop 2
	global_load_dword v7, v1, s[8:9] sc1
	v_readlane_b32 s8, v254, 43
	v_readlane_b32 s9, v254, 44
	s_waitcnt vmcnt(0)
	v_add_u32_e32 v17, v17, v7
	s_nop 2
	global_load_dword v8, v1, s[8:9] sc1
	v_readlane_b32 s8, v254, 45
	v_readlane_b32 s9, v254, 46
	s_waitcnt vmcnt(0)
	v_add_u32_e32 v17, v17, v8
	s_nop 2
	global_load_dword v9, v1, s[8:9] sc1
	v_readlane_b32 s8, v254, 47
	v_readlane_b32 s9, v254, 48
	s_waitcnt vmcnt(0)
	v_add_u32_e32 v17, v17, v9
	s_nop 2
	global_load_dword v10, v1, s[8:9] sc1
	v_readlane_b32 s8, v254, 49
	v_readlane_b32 s9, v254, 50
	s_waitcnt vmcnt(0)
	v_add_u32_e32 v17, v17, v10
	s_nop 2
	global_load_dword v11, v1, s[8:9] sc1
	v_readlane_b32 s8, v254, 51
	v_readlane_b32 s9, v254, 52
	s_nop 4
	global_load_dword v12, v1, s[8:9] sc1
	global_load_dword v13, v1, s[68:69] sc1
	global_load_dword v14, v1, s[74:75] sc1
	global_load_dword v15, v1, s[64:65] sc1
	global_load_dword v16, v1, s[72:73] sc1
	s_mov_b64 s[8:9], -1
	s_waitcnt vmcnt(5)
	v_add_u32_e32 v17, v17, v11
	s_waitcnt vmcnt(4)
	v_add_u32_e32 v17, v17, v12
	s_waitcnt vmcnt(3)
	v_add_u32_e32 v17, v17, v13
	s_waitcnt vmcnt(2)
	v_add_u32_e32 v17, v17, v14
	s_waitcnt vmcnt(1)
	v_add_u32_e32 v17, v17, v15
	s_waitcnt vmcnt(0)
	v_add_u32_e32 v17, v17, v16
	v_cmp_eq_u32_e32 vcc, s56, v17
	s_cbranch_vccnz .LBB0_835
	s_and_b32 s8, s15, 0xff
	s_cmp_eq_u32 s8, 0
	s_mov_b64 s[8:9], -1
	s_mov_b64 s[12:13], -1
	s_nop 0
	s_cbranch_scc0 .LBB0_840
	v_readlane_b32 s8, v254, 27
	v_readlane_b32 s9, v254, 28
	s_nop 4
	global_load_dword v17, v1, s[8:9] sc1
	s_waitcnt vmcnt(0)
	v_cmp_eq_u32_e32 vcc, 0, v17
	s_cbranch_vccnz .LBB0_842
	s_mov_b64 s[12:13], 0
	s_mov_b64 s[8:9], -1

; DI unsigned xb_ld(unsigned* p)              { return __hip_atomic_load(p, __ATOMIC_RELAXED, __HIP_MEMORY_SCOPE_AGENT); }
; DI unsigned xb_add(unsigned* p, unsigned v) { return __hip_atomic_fetch_add(p, v, __ATOMIC_RELAXED, __HIP_MEMORY_SCOPE_AGENT); }
; #define XB_SPIN(cond, bar) do { unsigned _sp = 0; while (cond) { __builtin_amdgcn_s_sleep(1); \
;     if ((++_sp & 255u) == 0u) { if (xb_ld(&(bar)[XB_TMO])) break; if (_sp > XB_SPIN_CAP) { atomicAdd(&(bar)[XB_TMO], 1u); break; } } } } while (0)
; DI void xcd_barrier(char* ws_, char* smem_) {
;     ...
;       else XB_SPIN(xb_ld(&bar[XB_TOPGEN]) == tg, bar);
;       __builtin_amdgcn_fence(__ATOMIC_ACQUIRE, "agent");
;       xb_add(&bar[XB_XGEN(b.x)], 1u);
;       asm volatile("s_waitcnt vmcnt(0)" ::: "memory");
;     } else {
;       XB_SPIN(xb_ld(&bar[XB_XGEN(b.x)]) == gen, bar);
.LBB0_854:
	s_and_b32 s22, s26, 0xff
	s_mov_b64 s[20:21], -1
	s_cmp_lg_u32 s22, 0
	s_mov_b64 s[24:25], -1
	s_nop 0
	s_cbranch_scc1 .LBB0_857
	v_readlane_b32 s22, v254, 27
	v_readlane_b32 s23, v254, 28
	s_nop 4
	global_load_dword v2, v1, s[22:23] sc1
	s_waitcnt vmcnt(0)
	v_cmp_eq_u32_e32 vcc, 0, v2
	s_cbranch_vccnz .LBB0_859
	s_mov_b64 s[24:25], 0
	s_mov_b64 s[22:23], -1

; DI unsigned xb_ld(unsigned* p)              { return __hip_atomic_load(p, __ATOMIC_RELAXED, __HIP_MEMORY_SCOPE_AGENT); }
; DI unsigned xb_add(unsigned* p, unsigned v) { return __hip_atomic_fetch_add(p, v, __ATOMIC_RELAXED, __HIP_MEMORY_SCOPE_AGENT); }
; #define XB_SPIN(cond, bar) do { unsigned _sp = 0; while (cond) { __builtin_amdgcn_s_sleep(1); \
;     if ((++_sp & 255u) == 0u) { if (xb_ld(&(bar)[XB_TMO])) break; if (_sp > XB_SPIN_CAP) { atomicAdd(&(bar)[XB_TMO], 1u); break; } } } } while (0)
; DI void xcd_barrier(char* ws_, char* smem_) {
;     ...
;       else XB_SPIN(xb_ld(&bar[XB_TOPGEN]) == tg, bar);
;       __builtin_amdgcn_fence(__ATOMIC_ACQUIRE, "agent");
;       xb_add(&bar[XB_XGEN(b.x)], 1u);
;       asm volatile("s_waitcnt vmcnt(0)" ::: "memory");
;     } else {
;       XB_SPIN(xb_ld(&bar[XB_XGEN(b.x)]) == gen, bar);
.LBB0_871:
	s_and_b32 s20, s24, 0xff
	s_mov_b64 s[18:19], -1
	s_cmp_lg_u32 s20, 0
	s_mov_b64 s[22:23], -1
	s_nop 0
	s_cbranch_scc1 .LBB0_874
	v_readlane_b32 s20, v254, 27
	v_readlane_b32 s21, v254, 28
	s_nop 4
	global_load_dword v2, v1, s[20:21] sc1
	s_waitcnt vmcnt(0)
	v_cmp_eq_u32_e32 vcc, 0, v2
	s_cbranch_vccnz .LBB0_876
	s_mov_b64 s[22:23], 0
	s_mov_b64 s[20:21], -1
